# group-mode barrier arrive publishes its generation word with a plain store (L2-resident) instead of sc1 write-through
# speedup vs baseline: 1.0129x; 1.0040x over previous
; __device__ __forceinline__ unsigned xb_add(unsigned* p, unsigned v) { return __hip_atomic_fetch_add(p, v, __ATOMIC_RELAXED, __HIP_MEMORY_SCOPE_AGENT); }
; __device__ __forceinline__ void xcd_barrier_arrive(const XcdBarrier& b) {
;     ...
;         if (lane == 0) {
;             const unsigned old = xb_add(&bar[grp ? XB_GSUB(g) : XB_XSUB(g)], 1u);
;             const unsigned tgt = old / nloc + 1u;
;             if (old + 1u == tgt * nloc) {
;                 if (!grp) __builtin_amdgcn_fence(__ATOMIC_RELEASE, "agent");
;                 asm volatile("s_waitcnt vmcnt(0)" ::: "memory");
;                 __hip_atomic_store(&bar[grp ? XB_GTOP(g) : XB_TOP + g], tgt, __ATOMIC_RELAXED, __HIP_MEMORY_SCOPE_AGENT);
;             }
;             b.st[2] = tgt;
.LBB0_774:
	s_addk_i32 s11, 0x1200
	s_addk_i32 s10, 0xd00
	s_and_b64 s[4:5], s[4:5], exec
	s_cselect_b32 s96, s10, s11
	s_cselect_b32 s98, 1, 0
	s_waitcnt vmcnt(0)
	s_lshl_b64 s[4:5], s[96:97], 2
	v_readlane_b32 s8, v251, 4
	v_readlane_b32 s9, v251, 5
	s_add_u32 s4, s8, s4
	s_addc_u32 s5, s9, s5
	s_cmp_eq_u32 s98, 0
	s_cbranch_scc1 .Larrive_grp_store
	global_store_dword v33, v1, s[4:5] sc1
	s_branch .Larrive_store_done
.Larrive_grp_store:
	global_store_dword v33, v1, s[4:5]
.Larrive_store_done:
.LBB0_775:
	s_or_b64 exec, exec, s[6:7]
	v_readlane_b32 s4, v254, 16
	s_nop 1
	v_mov_b32_e32 v0, s4
	ds_write_b32 v0, v1
